# v32 + priority window extended over all 8 QK MFMAs of each memory-attention tile
# baseline (speedup 1.0000x reference)
; DI u32x2 pack4(float a, float b, float c, float d) { u32x2 r; r.x = pack2(a, b); r.y = pack2(c, d); return r; }
; template <int DK, int MODE> ...
;     ...
;   bf16x8 qf[NKS];
;   {
;     const bf16_t* qp = Q + (size_t)qpos * DK + h * 8;
; #pragma unroll
;     for (int ks = 0; ks < NKS; ++ks) qf[ks] = *(const bf16x8*)(qp + ks * 16);
; #pragma unroll
;     for (int ks = 0; ks < NKS; ++ks) asm volatile("" : "+v"(qf[ks]));
;   }
;   float Fref = 0.f;
;   if (MODE == 1) Fref = F[qb * 128];
;   f32x16 o0, o1;
; #pragma unroll
;   for (int e = 0; e < 16; ++e) { o0[e] = 0.f; o1[e] = 0.f; }
;   float m = -1e30f, lsum = 0.f, R = 1.f;
;   u32x4 rk[NKL], rv[2];
;   float rf = 0.f;
;   auto gload = [&](int jt) {
; #pragma unroll
;     for (int i = 0; i < NKL; ++i) {
;       const int id = tid + 256 * i, row = id / KCH, ch = id % KCH;
;       rk[i] = *(const u32x4*)(K + (size_t)(jt * 64 + row) * DK + ch * 8);
;     }
; #pragma unroll
;     for (int i = 0; i < 2; ++i) {
;       const int id = tid + 256 * i, row = id >> 3, ch = id & 7;
;       rv[i] = *(const u32x4*)(Vt + (size_t)row * Skv + jt * 64 + ch * 8);
;     }
;     ...
;   const bf16_t* gp = gate + (size_t)qpos * 1024;
;   bf16_t* op = outp + (size_t)qpos * 1024;
; #pragma unroll
;   for (int dt = 0; dt < 2; ++dt)
; #pragma unroll
;     for (int g = 0; g < 4; ++g) {
;       const int dv = 32 * dt + 8 * g + 4 * h;
;       const u32x2 gv = *(const u32x2*)(gp + dv);
;       const f32x16& o = dt ? o1 : o0;
;       const float g0 = __uint_as_float(gv.x << 16), g1 = __uint_as_float(gv.x & 0xffff0000u), g2 = __uint_as_float(gv.y << 16), g3 = __uint_as_float(gv.y & 0xffff0000u);
;       *(u32x2*)(op + dv) = pack4(o[4 * g] * inv * g0, o[4 * g + 1] * inv * g1, o[4 * g + 2] * inv * g2, o[4 * g + 3] * inv * g3);
;     }
.LBB0_588:
	s_lshl_b32 s2, s28, 7
	s_and_b32 s2, s2, 0x180
	s_add_u32 s6, s11, s2
	v_readlane_b32 s4, v214, 5
	s_addc_u32 s7, s4, 0
	v_lshlrev_b64 v[2:3], 11, v[132:133]
	v_lshl_add_u64 v[4:5], s[6:7], 0, v[2:3]
	v_lshlrev_b32_e32 v0, 1, v135
	v_lshl_add_u64 v[4:5], v[4:5], 0, v[0:1]
	global_load_dwordx2 v[6:7], v[4:5], off offset:512
	v_readlane_b32 s4, v214, 6
	s_add_u32 s4, s4, s2
	v_readlane_b32 s2, v214, 7
	s_addc_u32 s5, s2, 0
	v_lshl_add_u64 v[2:3], s[4:5], 0, v[2:3]
	v_lshl_add_u64 v[2:3], v[2:3], 0, v[0:1]
	s_lshl_b32 s2, s28, 14
	v_readlane_b32 s8, v214, 8
	s_add_i32 s2, s2, s8
	s_lshl_b32 s16, s20, 1
	s_movk_i32 s54, 0x90
	s_waitcnt vmcnt(0)
	v_lshlrev_b32_e32 v8, 16, v6
	v_and_b32_e32 v9, 0xffff0000, v6
	v_lshlrev_b32_e32 v6, 16, v7
	v_and_b32_e32 v7, 0xffff0000, v7
	v_pk_mul_f32 v[8:9], v[32:33], v[8:9]
	v_pk_mul_f32 v[6:7], v[34:35], v[6:7]
	v_cvt_pk_bf16_f32 v8, v8, v9
	v_cvt_pk_bf16_f32 v9, v6, v7
	global_load_dwordx2 v[6:7], v[4:5], off offset:528
	s_nop 0
	global_store_dwordx2 v[2:3], v[8:9], off offset:512
	s_waitcnt vmcnt(1)
	v_lshlrev_b32_e32 v8, 16, v6
	v_and_b32_e32 v9, 0xffff0000, v6
	v_lshlrev_b32_e32 v6, 16, v7
	v_and_b32_e32 v7, 0xffff0000, v7
	v_pk_mul_f32 v[8:9], v[36:37], v[8:9]
	v_pk_mul_f32 v[6:7], v[38:39], v[6:7]
	v_cvt_pk_bf16_f32 v8, v8, v9
	v_cvt_pk_bf16_f32 v9, v6, v7
	global_load_dwordx2 v[6:7], v[4:5], off offset:544
	s_nop 0
	global_store_dwordx2 v[2:3], v[8:9], off offset:528
	s_waitcnt vmcnt(1)
	v_lshlrev_b32_e32 v8, 16, v6
	v_and_b32_e32 v9, 0xffff0000, v6
	v_lshlrev_b32_e32 v6, 16, v7
	v_and_b32_e32 v7, 0xffff0000, v7
	v_pk_mul_f32 v[8:9], v[40:41], v[8:9]
	v_pk_mul_f32 v[6:7], v[42:43], v[6:7]
	v_cvt_pk_bf16_f32 v8, v8, v9
	v_cvt_pk_bf16_f32 v9, v6, v7
	global_load_dwordx2 v[6:7], v[4:5], off offset:560
	s_nop 0
	global_store_dwordx2 v[2:3], v[8:9], off offset:544
	s_waitcnt vmcnt(1)
	v_lshlrev_b32_e32 v8, 16, v6
	v_and_b32_e32 v9, 0xffff0000, v6
	v_lshlrev_b32_e32 v6, 16, v7
	v_and_b32_e32 v7, 0xffff0000, v7
	v_pk_mul_f32 v[8:9], v[44:45], v[8:9]
	v_pk_mul_f32 v[6:7], v[46:47], v[6:7]
	v_cvt_pk_bf16_f32 v8, v8, v9
	v_cvt_pk_bf16_f32 v9, v6, v7
	global_load_dwordx2 v[6:7], v[4:5], off offset:576
	s_nop 0
	global_store_dwordx2 v[2:3], v[8:9], off offset:560
	s_waitcnt vmcnt(1)
	v_lshlrev_b32_e32 v8, 16, v6
	v_and_b32_e32 v9, 0xffff0000, v6
	v_lshlrev_b32_e32 v6, 16, v7
	v_and_b32_e32 v7, 0xffff0000, v7
	v_pk_mul_f32 v[8:9], v[16:17], v[8:9]
	v_pk_mul_f32 v[6:7], v[18:19], v[6:7]
	v_cvt_pk_bf16_f32 v8, v8, v9
	v_cvt_pk_bf16_f32 v9, v6, v7
	global_load_dwordx2 v[6:7], v[4:5], off offset:592
	s_nop 0
	global_store_dwordx2 v[2:3], v[8:9], off offset:576
	s_waitcnt vmcnt(1)
	v_lshlrev_b32_e32 v8, 16, v6
	v_and_b32_e32 v9, 0xffff0000, v6
	v_lshlrev_b32_e32 v6, 16, v7
	v_and_b32_e32 v7, 0xffff0000, v7
	v_pk_mul_f32 v[8:9], v[20:21], v[8:9]
	v_pk_mul_f32 v[6:7], v[22:23], v[6:7]
	v_cvt_pk_bf16_f32 v8, v8, v9
	v_cvt_pk_bf16_f32 v9, v6, v7
	global_load_dwordx2 v[6:7], v[4:5], off offset:608
	s_nop 0
	global_load_dwordx2 v[4:5], v[4:5], off offset:624
	s_nop 0
	global_store_dwordx2 v[2:3], v[8:9], off offset:592
	s_waitcnt vmcnt(2)
	v_lshlrev_b32_e32 v8, 16, v6
	v_and_b32_e32 v9, 0xffff0000, v6
	v_lshlrev_b32_e32 v6, 16, v7
	v_and_b32_e32 v7, 0xffff0000, v7
	v_pk_mul_f32 v[8:9], v[24:25], v[8:9]
	v_pk_mul_f32 v[6:7], v[26:27], v[6:7]
	v_cvt_pk_bf16_f32 v8, v8, v9
	v_cvt_pk_bf16_f32 v9, v6, v7
	s_waitcnt vmcnt(1)
	v_lshlrev_b32_e32 v6, 16, v4
	v_and_b32_e32 v7, 0xffff0000, v4
	v_lshlrev_b32_e32 v4, 16, v5
	v_and_b32_e32 v5, 0xffff0000, v5
	v_pk_mul_f32 v[6:7], v[28:29], v[6:7]
	v_pk_mul_f32 v[4:5], v[30:31], v[4:5]
	v_cvt_pk_bf16_f32 v6, v6, v7
	v_cvt_pk_bf16_f32 v7, v4, v5
	global_store_dwordx2 v[2:3], v[8:9], off offset:608
	global_store_dwordx2 v[2:3], v[6:7], off offset:624
	s_barrier
	s_load_dwordx4 s[40:43], s[18:19], 0x118
	s_load_dwordx2 s[12:13], s[18:19], 0x128
	v_mov_b32_e32 v28, v188
	s_waitcnt lgkmcnt(0)
	s_add_u32 s28, s40, s16
	s_addc_u32 s29, s41, 0
	s_lshl_b32 s2, s2, 1
	s_add_u32 s22, s42, s2
	s_addc_u32 s23, s43, 0
	s_add_u32 s24, s12, s2
	v_readfirstlane_b32 s2, v28
	s_addc_u32 s25, s13, 0
	s_ashr_i32 s2, s2, 1
	s_andn2_b32 s2, s2, 31
	v_and_b32_e32 v36, 31, v28
	s_add_i32 s2, s2, s21
	v_or_b32_e32 v130, s2, v36
	v_ashrrev_i32_e32 v131, 31, v130
	v_bfe_u32 v149, v28, 5, 1
	v_lshlrev_b64 v[2:3], 7, v[130:131]
	v_lshl_add_u64 v[2:3], s[28:29], 0, v[2:3]
	v_lshlrev_b32_e32 v0, 4, v149
	v_lshl_add_u64 v[2:3], v[2:3], 0, v[0:1]
	global_load_dwordx4 v[78:81], v[2:3], off
	global_load_dwordx4 v[74:77], v[2:3], off offset:32
	global_load_dwordx4 v[70:73], v[2:3], off offset:64
	global_load_dwordx4 v[66:69], v[2:3], off offset:96
	v_ashrrev_i32_e32 v2, 31, v28
	v_lshrrev_b32_e32 v2, 29, v2
	v_add_u32_e32 v2, v28, v2
	v_ashrrev_i32_e32 v18, 3, v2
	v_ashrrev_i32_e32 v19, 31, v18
	v_lshlrev_b64 v[10:11], 7, v[18:19]
	v_add_u32_e32 v19, 0x100, v28
	v_ashrrev_i32_e32 v6, 31, v19
	v_and_b32_e32 v2, -8, v2
	v_lshrrev_b32_e32 v6, 29, v6
	v_sub_u32_e32 v37, v28, v2
	v_add_u32_e32 v6, v19, v6
	v_lshlrev_b32_e32 v4, 3, v37
	v_ashrrev_i32_e32 v24, 3, v6
	v_and_b32_e32 v6, -8, v6
	v_ashrrev_i32_e32 v5, 31, v4
	v_sub_u32_e32 v38, v19, v6
	v_lshl_add_u64 v[2:3], s[22:23], 0, v[10:11]
	v_lshlrev_b64 v[14:15], 1, v[4:5]
	v_ashrrev_i32_e32 v25, 31, v24
	v_lshlrev_b32_e32 v8, 3, v38
	v_lshl_add_u64 v[2:3], v[2:3], 0, v[14:15]
	v_lshlrev_b64 v[12:13], 7, v[24:25]
	v_ashrrev_i32_e32 v9, 31, v8
	global_load_dwordx4 v[2:5], v[2:3], off
	v_lshl_add_u64 v[6:7], s[22:23], 0, v[12:13]
	v_lshlrev_b64 v[16:17], 1, v[8:9]
	v_lshl_add_u64 v[6:7], v[6:7], 0, v[16:17]
	global_load_dwordx4 v[6:9], v[6:7], off
	v_ashrrev_i32_e32 v20, 3, v28
	v_ashrrev_i32_e32 v34, 3, v19
	v_ashrrev_i32_e32 v21, 31, v20
	v_ashrrev_i32_e32 v35, 31, v34
	v_lshlrev_b64 v[22:23], 9, v[20:21]
	v_lshlrev_b32_e32 v21, 4, v28
	v_lshlrev_b64 v[30:31], 9, v[34:35]
	v_lshl_add_u64 v[26:27], s[24:25], 0, v[22:23]
	v_and_b32_e32 v22, 0x70, v21
	v_mov_b32_e32 v23, v1
	v_lshl_add_u64 v[30:31], s[24:25], 0, v[30:31]
	v_lshl_add_u64 v[136:137], v[26:27], 0, v[22:23]
	v_lshl_add_u64 v[138:139], v[30:31], 0, v[22:23]
	global_load_dwordx4 v[26:29], v[136:137], off
	global_load_dwordx4 v[30:33], v[138:139], off
	v_mul_lo_u32 v18, v18, s54
	v_lshl_add_u32 v151, v37, 4, v18
	s_movk_i32 s2, 0x2000
	v_mad_u64_u32 v[132:133], s[12:13], v20, s54, v[22:23]
	v_mad_u64_u32 v[134:135], s[12:13], v34, s54, v[22:23]
	s_waitcnt vmcnt(3)
; #define MFMA(a, b, c) __builtin_amdgcn_mfma_f32_32x32x16_bf16((a), (b), (c), 0, 0, 0)
; template <int DK, int MODE> ...
;     ...
; #pragma unroll
;       for (int ks = 0; ks < NKS; ++ks) { kf0[ks] = *(const bf16x8*)(kb + ks * 16); kf1[ks] = *(const bf16x8*)(kb + 32 * LDK + ks * 16); }
;       if (MODE == 1) {
;         const float* fb = sF + cur * 64 + 4 * h;
; #pragma unroll
;         for (int g = 0; g < 4; ++g) {
;           const f32x4 f0 = *(const f32x4*)(fb + 8 * g), f1 = *(const f32x4*)(fb + 32 + 8 * g);
;           s0[4 * g] = f0.x; s0[4 * g + 1] = f0.y; s0[4 * g + 2] = f0.z; s0[4 * g + 3] = f0.w;
;           s1[4 * g] = f1.x; s1[4 * g + 1] = f1.y; s1[4 * g + 2] = f1.z; s1[4 * g + 3] = f1.w;
;         }
;       } else {
; #pragma unroll
;         for (int e = 0; e < 16; ++e) { s0[e] = 0.f; s1[e] = 0.f; }
;       }
;       __builtin_amdgcn_iglp_opt(0);
;       __builtin_amdgcn_s_setprio(1);
; #pragma unroll
;       for (int ks = 0; ks < NKS; ++ks) { s0 = MFMA(kf0[ks], qf[ks], s0); s1 = MFMA(kf1[ks], qf[ks], s1); }
;       __builtin_amdgcn_s_setprio(0);
;       const bf16_t* vb = sV + cur * 64 * 72 + l32 * 72 + h * 8;
;       bf16x8 vf0[4], vf1[4];
; #pragma unroll
;       for (int j = 0; j < 4; ++j) { vf0[j] = *(const bf16x8*)(vb + j * 16); vf1[j] = *(const bf16x8*)(vb + 32 * 72 + j * 16); }
;       __builtin_amdgcn_sched_barrier(0);
;       const bool need_mask = CAUSAL && (key0 + 63 >= tq0);
;       bf16x8 pf[4];
;       if (MODE != 2) {
;         if (need_mask) {
; #pragma unroll
;           for (int e = 0; e < 16; ++e) {
;             const int key = key0 + 8 * (e >> 2) + 4 * h + (e & 3);
;             if (key > qpos) s0[e] = -1e30f;
;             if (key + 32 > qpos) s1[e] = -1e30f;
;           }
;         }
;         float mx = s0[0];
; #pragma unroll
;         for (int e = 1; e < 16; ++e) mx = fmaxf(mx, s0[e]);
; #pragma unroll
;         for (int e = 0; e < 16; ++e) mx = fmaxf(mx, s1[e]);
;         mx = fmaxf(mx, __shfl_xor(mx, 32));
;         if (__any(mx > m + 8.f)) {
;           const float mnew = fmaxf(m, mx);
;           const float alpha = __builtin_amdgcn_exp2f(m - mnew);
;           m = mnew; lsum *= alpha;
; #pragma unroll
;           for (int e = 0; e < 16; ++e) { o0[e] *= alpha; o1[e] *= alpha; }
;         }
;         float ps0 = 0.f, ps1 = 0.f, ps2 = 0.f, ps3 = 0.f;
; #pragma unroll
;         for (int e = 0; e < 16; e += 4) {
	ds_write_b128 v151, v[2:5]
	v_mul_lo_u32 v2, v24, s54
	v_lshl_add_u32 v152, v38, 4, v2
	v_lshl_add_u64 v[2:3], s[22:23], 0, v[14:15]
	s_waitcnt vmcnt(2)
	ds_write_b128 v152, v[6:9]
	v_mul_u32_u24_e32 v6, 0x48, v36
	v_and_b32_e32 v7, 64, v192
	v_lshl_add_u32 v0, v6, 1, v0
	v_xor_b32_e32 v6, 32, v192
	v_add_u32_e32 v7, 64, v7
	v_cmp_lt_i32_e32 vcc, v6, v7
	v_lshl_add_u64 v[140:141], v[2:3], 0, v[10:11]
	v_lshl_add_u64 v[4:5], s[22:23], 0, v[16:17]
	v_cndmask_b32_e32 v6, v192, v6, vcc
	v_add_co_u32_e32 v2, vcc, s2, v140
	v_lshl_add_u64 v[142:143], v[4:5], 0, v[12:13]
	s_nop 0
	v_addc_co_u32_e32 v3, vcc, 0, v141, vcc
	s_waitcnt vmcnt(1)
	ds_write_b128 v132, v[26:29] offset:18432
	s_waitcnt vmcnt(0)
	ds_write_b128 v134, v[30:33] offset:18432
	s_waitcnt lgkmcnt(0)
	s_barrier
	global_load_dwordx4 v[50:53], v[2:3], off
	v_add_co_u32_e32 v2, vcc, s2, v142
	global_load_dwordx4 v[58:61], v[136:137], off offset:128
	s_nop 0
	v_addc_co_u32_e32 v3, vcc, 0, v143, vcc
	global_load_dwordx4 v[54:57], v[2:3], off
	global_load_dwordx4 v[62:65], v[138:139], off offset:128
	ds_read_b128 v[2:5], v0 offset:4608
	ds_read_b128 v[18:21], v0
	ds_read_b128 v[34:37], v0 offset:32
	ds_read_b128 v[22:25], v0 offset:4640
	ds_read_b128 v[38:41], v0 offset:64
	ds_read_b128 v[26:29], v0 offset:4672
	ds_read_b128 v[42:45], v0 offset:96
	ds_read_b128 v[30:33], v0 offset:4704
	v_lshlrev_b32_e32 v133, 2, v6
	s_setprio 1
	s_waitcnt lgkmcnt(7)
	v_mfma_f32_32x32x16_bf16 v[2:17], v[2:5], v[78:81], 0
	s_waitcnt lgkmcnt(4)
	v_mfma_f32_32x32x16_bf16 v[2:17], v[22:25], v[74:77], v[2:17]
	s_waitcnt lgkmcnt(2)
	v_mfma_f32_32x32x16_bf16 v[2:17], v[26:29], v[70:73], v[2:17]
	s_waitcnt lgkmcnt(0)
	v_mfma_f32_32x32x16_bf16 v[2:17], v[30:33], v[66:69], v[2:17]
	v_mfma_f32_32x32x16_bf16 v[18:33], v[18:21], v[78:81], 0
	ds_read_b128 v[82:85], v0 offset:18432
	ds_read_b128 v[86:89], v0 offset:18464
	ds_read_b128 v[90:93], v0 offset:23040
	ds_read_b128 v[94:97], v0 offset:23072
	ds_read_b128 v[98:101], v0 offset:18496
	ds_read_b128 v[102:105], v0 offset:18528
	ds_read_b128 v[106:109], v0 offset:23104
	v_mfma_f32_32x32x16_bf16 v[18:33], v[34:37], v[74:77], v[18:33]
	ds_read_b128 v[110:113], v0 offset:23136
	v_mfma_f32_32x32x16_bf16 v[18:33], v[38:41], v[70:73], v[18:33]
	v_mfma_f32_32x32x16_bf16 v[18:33], v[42:45], v[66:69], v[18:33]
	s_setprio 0
	s_nop 11
	v_max_f32_e32 v34, v19, v19
	v_max_f32_e32 v35, v18, v18
	v_max_f32_e32 v34, v35, v34
	v_max3_f32 v34, v34, v20, v21
	v_max3_f32 v34, v34, v22, v23
	v_max3_f32 v34, v34, v24, v25
	v_max3_f32 v34, v34, v26, v27
	v_max3_f32 v34, v34, v28, v29
	v_max3_f32 v34, v34, v30, v31
	v_max3_f32 v34, v34, v32, v33
	v_max3_f32 v34, v34, v2, v3
	v_max3_f32 v34, v34, v4, v5
	v_max3_f32 v34, v34, v6, v7
	v_max3_f32 v34, v34, v8, v9
	v_max3_f32 v34, v34, v10, v11
	v_max3_f32 v34, v34, v12, v13
	v_max3_f32 v34, v34, v14, v15
	v_max3_f32 v34, v34, v16, v17
	ds_bpermute_b32 v35, v133, v34
	s_mov_b32 s2, 0xf149f2ca
	s_waitcnt lgkmcnt(0)
	v_max_f32_e32 v35, v35, v35
	v_max_f32_e32 v34, v34, v35
	v_cmp_lt_f32_e32 vcc, s2, v34
	s_cmp_eq_u64 vcc, 0
	v_max_f32_e32 v114, 0xf149f2ca, v34
	s_cselect_b64 vcc, -1, 0
	v_cndmask_b32_e32 v135, v114, v198, vcc
	v_sub_f32_e32 v19, v19, v135
	v_sub_f32_e32 v35, 0xf149f2ca, v114
	v_sub_f32_e32 v18, v18, v135
	v_exp_f32_e32 v114, v19
	v_sub_f32_e32 v19, v20, v135
	v_sub_f32_e32 v20, v21, v135
	v_sub_f32_e32 v21, v23, v135
	v_exp_f32_e32 v18, v18
	v_exp_f32_e32 v19, v19
	v_exp_f32_e32 v115, v20
	v_sub_f32_e32 v20, v22, v135
	v_exp_f32_e32 v22, v21
	v_sub_f32_e32 v21, v24, v135
	v_sub_f32_e32 v23, v25, v135
	v_sub_f32_e32 v25, v27, v135
	v_exp_f32_e32 v20, v20
	v_exp_f32_e32 v21, v21
	v_exp_f32_e32 v23, v23
	v_sub_f32_e32 v24, v26, v135
	v_exp_f32_e32 v26, v25
	v_sub_f32_e32 v25, v28, v135
	v_sub_f32_e32 v27, v29, v135
	v_sub_f32_e32 v29, v31, v135
	v_exp_f32_e32 v24, v24
	v_exp_f32_e32 v25, v25
	v_exp_f32_e32 v27, v27
	v_sub_f32_e32 v28, v30, v135
	v_exp_f32_e32 v30, v29
	v_sub_f32_e32 v29, v32, v135
	v_sub_f32_e32 v31, v33, v135
	v_sub_f32_e32 v3, v3, v135
	v_exp_f32_e32 v28, v28
	v_exp_f32_e32 v29, v29
	v_exp_f32_e32 v31, v31
	v_sub_f32_e32 v2, v2, v135
	v_exp_f32_e32 v32, v3
	v_sub_f32_e32 v3, v4, v135
	v_sub_f32_e32 v4, v5, v135
	v_sub_f32_e32 v5, v7, v135
	v_sub_f32_e32 v7, v9, v135
	v_sub_f32_e32 v9, v11, v135
	v_sub_f32_e32 v11, v13, v135
	v_sub_f32_e32 v13, v15, v135
	v_exp_f32_e32 v2, v2
	v_exp_f32_e32 v3, v3
	v_exp_f32_e32 v33, v4
	v_sub_f32_e32 v4, v6, v135
	v_exp_f32_e32 v6, v5
	v_sub_f32_e32 v5, v8, v135
	v_sub_f32_e32 v8, v10, v135
	v_exp_f32_e32 v10, v9
	v_sub_f32_e32 v9, v12, v135
	v_sub_f32_e32 v12, v14, v135
	v_exp_f32_e32 v14, v13
	v_sub_f32_e32 v13, v16, v135
	v_sub_f32_e32 v15, v17, v135
	v_pk_add_f32 v[16:17], v[18:19], 0 op_sel_hi:[1,0]
	v_pk_add_f32 v[116:117], v[114:115], 0 op_sel_hi:[1,0]
	v_exp_f32_e32 v4, v4
	v_exp_f32_e32 v5, v5
	v_exp_f32_e32 v7, v7
	v_pk_add_f32 v[16:17], v[20:21], v[16:17]
	v_pk_add_f32 v[116:117], v[22:23], v[116:117]
	v_exp_f32_e32 v8, v8
	v_exp_f32_e32 v9, v9
	v_exp_f32_e32 v11, v11
	v_pk_add_f32 v[16:17], v[24:25], v[16:17]
	v_pk_add_f32 v[116:117], v[26:27], v[116:117]
	v_exp_f32_e32 v35, v35
	v_exp_f32_e32 v12, v12
	v_exp_f32_e32 v13, v13
	v_exp_f32_e32 v15, v15
	v_pk_add_f32 v[16:17], v[28:29], v[16:17]
	v_pk_add_f32 v[154:155], v[30:31], v[116:117]
	v_cvt_pk_bf16_f32 v118, v2, v32
	v_cvt_pk_bf16_f32 v119, v3, v33
	v_pk_add_f32 v[2:3], v[2:3], v[16:17]
	v_pk_add_f32 v[16:17], v[32:33], v[154:155]
	v_cvt_pk_bf16_f32 v120, v4, v6
	v_cvt_pk_bf16_f32 v121, v5, v7
	v_pk_add_f32 v[2:3], v[4:5], v[2:3]
	v_pk_add_f32 v[4:5], v[6:7], v[16:17]
	v_pk_add_f32 v[2:3], v[8:9], v[2:3]
; #define MFMA(a, b, c) __builtin_amdgcn_mfma_f32_32x32x16_bf16((a), (b), (c), 0, 0, 0)
; DI unsigned pack2(float a, float b) { f32x2 v = {a, b}; return __builtin_bit_cast(unsigned, __builtin_convertvector(v, bf16v2)); }
; template <int DK, int MODE> ...
;     ...
;         float mx = s0[0];
; #pragma unroll
;         for (int e = 1; e < 16; ++e) mx = fmaxf(mx, s0[e]);
; #pragma unroll
;         for (int e = 0; e < 16; ++e) mx = fmaxf(mx, s1[e]);
;         mx = fmaxf(mx, __shfl_xor(mx, 32));
;         if (__any(mx > m + 8.f)) {
;           const float mnew = fmaxf(m, mx);
;           const float alpha = __builtin_amdgcn_exp2f(m - mnew);
;           m = mnew; lsum *= alpha;
; #pragma unroll
;           for (int e = 0; e < 16; ++e) { o0[e] *= alpha; o1[e] *= alpha; }
;         }
;     ...
; #pragma unroll
;       for (int j = 0; j < 2; ++j) {
;         u32x4 a, b;
;         a.x = pack2(s0[8 * j], s0[8 * j + 1]); a.y = pack2(s0[8 * j + 2], s0[8 * j + 3]); a.z = pack2(s0[8 * j + 4], s0[8 * j + 5]); a.w = pack2(s0[8 * j + 6], s0[8 * j + 7]);
;         b.x = pack2(s1[8 * j], s1[8 * j + 1]); b.y = pack2(s1[8 * j + 2], s1[8 * j + 3]); b.z = pack2(s1[8 * j + 4], s1[8 * j + 5]); b.w = pack2(s1[8 * j + 6], s1[8 * j + 7]);
;         pf[j] = __builtin_bit_cast(bf16x8, a); pf[2 + j] = __builtin_bit_cast(bf16x8, b);
;       }
;       __builtin_amdgcn_s_setprio(1);
; #pragma unroll
;       for (int j = 0; j < 4; ++j) { o0 = MFMA(vf0[j], pf[j], o0); o1 = MFMA(vf1[j], pf[j], o1); }
;       __builtin_amdgcn_s_setprio(0);
;     }
;     __builtin_amdgcn_sched_barrier(0);
;     if (more) swrite(cur ^ 1);
;     if (MODE == 2) { const int done = __all(R == 0.f); if (lane == 0) sFlag[cur * 4 + wave] = done; }
;     __syncthreads();
	v_pk_add_f32 v[4:5], v[10:11], v[4:5]
	v_mul_f32_e32 v34, 0, v35
	v_pk_add_f32 v[2:3], v[12:13], v[2:3]
	v_pk_add_f32 v[4:5], v[14:15], v[4:5]
	v_cndmask_b32_e64 v34, v34, 0, vcc
	v_pk_add_f32 v[2:3], v[2:3], v[4:5]
	v_mov_b32_e32 v35, v34
	v_mov_b32_e32 v36, v34
	v_mov_b32_e32 v37, v34
	v_mov_b32_e32 v38, v34
	v_mov_b32_e32 v39, v34
	v_mov_b32_e32 v40, v34
	v_mov_b32_e32 v41, v34
	v_mov_b32_e32 v42, v34
	v_mov_b32_e32 v43, v34
	v_mov_b32_e32 v44, v34
	v_mov_b32_e32 v45, v34
	v_mov_b32_e32 v46, v34
	v_mov_b32_e32 v47, v34
	v_mov_b32_e32 v48, v34
	v_mov_b32_e32 v49, v34
	v_cvt_pk_bf16_f32 v114, v18, v114
	v_cvt_pk_bf16_f32 v115, v19, v115
	v_cvt_pk_bf16_f32 v116, v20, v22
	v_cvt_pk_bf16_f32 v117, v21, v23
	v_cvt_pk_bf16_f32 v122, v24, v26
	v_cvt_pk_bf16_f32 v123, v25, v27
	v_cvt_pk_bf16_f32 v124, v28, v30
	v_cvt_pk_bf16_f32 v125, v29, v31
	v_cvt_pk_bf16_f32 v126, v8, v10
	v_cvt_pk_bf16_f32 v127, v9, v11
	v_cvt_pk_bf16_f32 v128, v12, v14
	v_cvt_pk_bf16_f32 v129, v13, v15
	v_add_f32_e32 v153, v2, v3
	s_setprio 1
	v_mov_b64_e32 v[2:3], v[34:35]
	v_mov_b64_e32 v[4:5], v[36:37]
	v_mov_b64_e32 v[6:7], v[38:39]
	v_mov_b64_e32 v[8:9], v[40:41]
	v_mov_b64_e32 v[10:11], v[42:43]
	v_mov_b64_e32 v[12:13], v[44:45]
	v_mov_b64_e32 v[14:15], v[46:47]
	v_mov_b64_e32 v[16:17], v[48:49]
	v_mfma_f32_32x32x16_bf16 v[18:33], v[82:85], v[114:117], v[34:49]
	v_add_f32_e32 v154, v34, v153
	v_mfma_f32_32x32x16_bf16 v[2:17], v[90:93], v[114:117], v[2:17]
	v_mfma_f32_32x32x16_bf16 v[18:33], v[86:89], v[122:125], v[18:33]
	v_mfma_f32_32x32x16_bf16 v[2:17], v[94:97], v[122:125], v[2:17]
	v_mfma_f32_32x32x16_bf16 v[18:33], v[98:101], v[118:121], v[18:33]
	v_mfma_f32_32x32x16_bf16 v[2:17], v[106:109], v[118:121], v[2:17]
	v_mfma_f32_32x32x16_bf16 v[18:33], v[102:105], v[126:129], v[18:33]
	v_mfma_f32_32x32x16_bf16 v[2:17], v[110:113], v[126:129], v[2:17]
	s_setprio 0
	s_movk_i32 s2, 0x4000
	v_add_co_u32_e32 v34, vcc, s2, v140
	s_waitcnt vmcnt(3)
	ds_write_b128 v151, v[50:53] offset:9216
	v_addc_co_u32_e32 v35, vcc, 0, v141, vcc
	s_waitcnt vmcnt(1)
	ds_write_b128 v152, v[54:57] offset:9216
	ds_write_b128 v132, v[58:61] offset:27648
	s_waitcnt vmcnt(0)
	ds_write_b128 v134, v[62:65] offset:27648
	s_waitcnt lgkmcnt(0)
	s_barrier
	global_load_dwordx4 v[82:85], v[34:35], off
	v_add_co_u32_e32 v34, vcc, s2, v142
	global_load_dwordx4 v[90:93], v[136:137], off offset:256
	s_nop 0
	v_addc_co_u32_e32 v35, vcc, 0, v143, vcc
	global_load_dwordx4 v[86:89], v[34:35], off
	global_load_dwordx4 v[94:97], v[138:139], off offset:256
	ds_read_b128 v[34:37], v0 offset:13824
	ds_read_b128 v[50:53], v0 offset:9216
	ds_read_b128 v[98:101], v0 offset:9248
	ds_read_b128 v[54:57], v0 offset:13856
	ds_read_b128 v[102:105], v0 offset:9280
	ds_read_b128 v[58:61], v0 offset:13888
	ds_read_b128 v[62:65], v0 offset:13920
	ds_read_b128 v[156:159], v0 offset:9312
	s_setprio 1
	s_waitcnt lgkmcnt(7)
	v_mfma_f32_32x32x16_bf16 v[34:49], v[34:37], v[78:81], 0
	s_waitcnt lgkmcnt(4)
	v_mfma_f32_32x32x16_bf16 v[34:49], v[54:57], v[74:77], v[34:49]
	s_waitcnt lgkmcnt(2)
	v_mfma_f32_32x32x16_bf16 v[34:49], v[58:61], v[70:73], v[34:49]
	s_waitcnt lgkmcnt(1)
	v_mfma_f32_32x32x16_bf16 v[34:49], v[62:65], v[66:69], v[34:49]
	v_mfma_f32_32x32x16_bf16 v[50:65], v[50:53], v[78:81], 0
	ds_read_b128 v[122:125], v0 offset:27648
	ds_read_b128 v[114:117], v0 offset:27680
	ds_read_b128 v[126:129], v0 offset:32256
	ds_read_b128 v[118:121], v0 offset:32288
	ds_read_b128 v[106:109], v0 offset:27712
	ds_read_b128 v[110:113], v0 offset:32320
	v_mfma_f32_32x32x16_bf16 v[50:65], v[98:101], v[74:77], v[50:65]
	ds_read_b128 v[98:101], v0 offset:32352
	v_mfma_f32_32x32x16_bf16 v[50:65], v[102:105], v[70:73], v[50:65]
	ds_read_b128 v[102:105], v0 offset:27744
	s_waitcnt lgkmcnt(8)
	v_mfma_f32_32x32x16_bf16 v[50:65], v[156:159], v[66:69], v[50:65]
	s_setprio 0
	s_nop 11
	v_max_f32_e32 v153, v51, v51
	v_max_f32_e32 v155, v50, v50
	v_max_f32_e32 v153, v155, v153
	v_max3_f32 v153, v153, v52, v53
	v_max3_f32 v153, v153, v54, v55
	v_max3_f32 v153, v153, v56, v57
	v_max3_f32 v153, v153, v58, v59
	v_max3_f32 v153, v153, v60, v61
	v_max3_f32 v153, v153, v62, v63
	v_max3_f32 v153, v153, v64, v65
	v_max3_f32 v153, v153, v34, v35
	v_max3_f32 v153, v153, v36, v37
	v_max3_f32 v153, v153, v38, v39
	v_max3_f32 v153, v153, v40, v41
	v_max3_f32 v153, v153, v42, v43
	v_max3_f32 v153, v153, v44, v45
	v_max3_f32 v153, v153, v46, v47
	v_max3_f32 v153, v153, v48, v49
	ds_bpermute_b32 v155, v133, v153
	s_waitcnt lgkmcnt(0)
	v_max_f32_e32 v155, v155, v155
	v_max_f32_e32 v155, v153, v155
	v_add_f32_e32 v153, 0x41000000, v135
	v_cmp_gt_f32_e32 vcc, v155, v153
	s_cbranch_vccz .LBB0_590
	v_max_f32_e32 v153, v155, v155
	v_max_f32_e32 v155, v135, v135
	v_max_f32_e32 v155, v155, v153
	v_sub_f32_e32 v135, v135, v155
	v_exp_f32_e32 v156, v135
	v_add_f32_e32 v153, 0x41000000, v155
	v_mov_b32_e32 v135, v155
	v_pk_mul_f32 v[32:33], v[32:33], v[156:157] op_sel_hi:[1,0]
	v_pk_mul_f32 v[30:31], v[30:31], v[156:157] op_sel_hi:[1,0]
	v_pk_mul_f32 v[28:29], v[28:29], v[156:157] op_sel_hi:[1,0]
	v_pk_mul_f32 v[26:27], v[26:27], v[156:157] op_sel_hi:[1,0]
	v_pk_mul_f32 v[24:25], v[24:25], v[156:157] op_sel_hi:[1,0]
	v_pk_mul_f32 v[22:23], v[22:23], v[156:157] op_sel_hi:[1,0]
	v_pk_mul_f32 v[20:21], v[20:21], v[156:157] op_sel_hi:[1,0]
	v_pk_mul_f32 v[18:19], v[18:19], v[156:157] op_sel_hi:[1,0]
	v_pk_mul_f32 v[16:17], v[16:17], v[156:157] op_sel_hi:[1,0]
	v_pk_mul_f32 v[14:15], v[14:15], v[156:157] op_sel_hi:[1,0]
	v_pk_mul_f32 v[12:13], v[12:13], v[156:157] op_sel_hi:[1,0]
	v_pk_mul_f32 v[10:11], v[10:11], v[156:157] op_sel_hi:[1,0]
	v_pk_mul_f32 v[8:9], v[8:9], v[156:157] op_sel_hi:[1,0]
	v_pk_mul_f32 v[6:7], v[6:7], v[156:157] op_sel_hi:[1,0]
	v_pk_mul_f32 v[4:5], v[4:5], v[156:157] op_sel_hi:[1,0]
	v_pk_mul_f32 v[2:3], v[2:3], v[156:157] op_sel_hi:[1,0]
	v_mul_f32_e32 v154, v154, v156
; #define MFMA(a, b, c) __builtin_amdgcn_mfma_f32_32x32x16_bf16((a), (b), (c), 0, 0, 0)
; DI unsigned pack2(float a, float b) { f32x2 v = {a, b}; return __builtin_bit_cast(unsigned, __builtin_convertvector(v, bf16v2)); }
; template <int DK, int MODE> ...
;     ...
;         float ps0 = 0.f, ps1 = 0.f, ps2 = 0.f, ps3 = 0.f;
; #pragma unroll
;         for (int e = 0; e < 16; e += 4) {
;           s0[e] = __builtin_amdgcn_exp2f(s0[e] - m); s0[e + 1] = __builtin_amdgcn_exp2f(s0[e + 1] - m); s0[e + 2] = __builtin_amdgcn_exp2f(s0[e + 2] - m); s0[e + 3] = __builtin_amdgcn_exp2f(s0[e + 3] - m);
;           ps0 += s0[e]; ps1 += s0[e + 1]; ps2 += s0[e + 2]; ps3 += s0[e + 3];
;         }
; #pragma unroll
;         for (int e = 0; e < 16; e += 4) {
;           s1[e] = __builtin_amdgcn_exp2f(s1[e] - m); s1[e + 1] = __builtin_amdgcn_exp2f(s1[e + 1] - m); s1[e + 2] = __builtin_amdgcn_exp2f(s1[e + 2] - m); s1[e + 3] = __builtin_amdgcn_exp2f(s1[e + 3] - m);
;           ps0 += s1[e]; ps1 += s1[e + 1]; ps2 += s1[e + 2]; ps3 += s1[e + 3];
;         }
;         lsum += (ps0 + ps1) + (ps2 + ps3);
;     ...
; #pragma unroll
;       for (int j = 0; j < 2; ++j) {
;         u32x4 a, b;
;         a.x = pack2(s0[8 * j], s0[8 * j + 1]); a.y = pack2(s0[8 * j + 2], s0[8 * j + 3]); a.z = pack2(s0[8 * j + 4], s0[8 * j + 5]); a.w = pack2(s0[8 * j + 6], s0[8 * j + 7]);
;         b.x = pack2(s1[8 * j], s1[8 * j + 1]); b.y = pack2(s1[8 * j + 2], s1[8 * j + 3]); b.z = pack2(s1[8 * j + 4], s1[8 * j + 5]); b.w = pack2(s1[8 * j + 6], s1[8 * j + 7]);
;         pf[j] = __builtin_bit_cast(bf16x8, a); pf[2 + j] = __builtin_bit_cast(bf16x8, b);
;       }
;       __builtin_amdgcn_s_setprio(1);
; #pragma unroll
;       for (int j = 0; j < 4; ++j) { o0 = MFMA(vf0[j], pf[j], o0); o1 = MFMA(vf1[j], pf[j], o1); }
;       __builtin_amdgcn_s_setprio(0);
;     }
;     __builtin_amdgcn_sched_barrier(0);
;     if (more) swrite(cur ^ 1);
;     if (MODE == 2) { const int done = __all(R == 0.f); if (lane == 0) sFlag[cur * 4 + wave] = done; }
;     __syncthreads();
.LBB0_590:
	v_sub_f32_e32 v51, v51, v135
	v_exp_f32_e32 v156, v51
	v_sub_f32_e32 v51, v52, v135
	v_sub_f32_e32 v52, v53, v135
	v_sub_f32_e32 v53, v55, v135
	v_sub_f32_e32 v55, v57, v135
	v_sub_f32_e32 v57, v59, v135
	v_sub_f32_e32 v59, v61, v135
	v_sub_f32_e32 v61, v63, v135
	v_sub_f32_e32 v34, v34, v135
	v_exp_f32_e32 v157, v52
	v_sub_f32_e32 v52, v54, v135
	v_exp_f32_e32 v54, v53
	v_sub_f32_e32 v53, v56, v135
	v_sub_f32_e32 v56, v58, v135
	v_exp_f32_e32 v58, v57
	v_sub_f32_e32 v57, v60, v135
	v_sub_f32_e32 v60, v62, v135
	v_exp_f32_e32 v62, v61
	v_sub_f32_e32 v61, v64, v135
	v_exp_f32_e32 v64, v34
	v_sub_f32_e32 v34, v35, v135
	v_exp_f32_e32 v158, v34
	v_sub_f32_e32 v34, v36, v135
	v_sub_f32_e32 v63, v65, v135
	v_exp_f32_e32 v65, v34
	v_sub_f32_e32 v34, v37, v135
	v_exp_f32_e32 v159, v34
	v_sub_f32_e32 v34, v38, v135
	v_exp_f32_e32 v160, v34
	v_sub_f32_e32 v34, v39, v135
	v_exp_f32_e32 v162, v34
	v_sub_f32_e32 v34, v40, v135
	v_exp_f32_e32 v161, v34
	v_sub_f32_e32 v34, v41, v135
	v_exp_f32_e32 v163, v34
	v_sub_f32_e32 v34, v42, v135
	v_exp_f32_e32 v164, v34
	v_sub_f32_e32 v34, v43, v135
	v_exp_f32_e32 v166, v34
	v_sub_f32_e32 v34, v44, v135
	v_sub_f32_e32 v50, v50, v135
	v_exp_f32_e32 v165, v34
	v_sub_f32_e32 v34, v45, v135
	v_exp_f32_e32 v50, v50
	v_exp_f32_e32 v51, v51
	v_exp_f32_e32 v167, v34
	v_sub_f32_e32 v34, v46, v135
	v_exp_f32_e32 v52, v52
	v_exp_f32_e32 v53, v53
	v_exp_f32_e32 v55, v55
	v_exp_f32_e32 v168, v34
	v_sub_f32_e32 v34, v47, v135
	v_exp_f32_e32 v56, v56
	v_exp_f32_e32 v57, v57
	v_exp_f32_e32 v59, v59
	v_exp_f32_e32 v170, v34
	v_sub_f32_e32 v34, v48, v135
	v_exp_f32_e32 v60, v60
	v_exp_f32_e32 v61, v61
	v_exp_f32_e32 v63, v63
	v_exp_f32_e32 v169, v34
	v_sub_f32_e32 v34, v49, v135
	v_exp_f32_e32 v171, v34
	v_pk_add_f32 v[34:35], v[50:51], 0 op_sel_hi:[1,0]
	v_pk_add_f32 v[36:37], v[156:157], 0 op_sel_hi:[1,0]
	v_pk_add_f32 v[34:35], v[52:53], v[34:35]
	v_pk_add_f32 v[36:37], v[54:55], v[36:37]
	v_pk_add_f32 v[34:35], v[56:57], v[34:35]
	v_pk_add_f32 v[36:37], v[58:59], v[36:37]
	v_pk_add_f32 v[172:173], v[60:61], v[34:35]
	v_pk_add_f32 v[174:175], v[62:63], v[36:37]
	v_cvt_pk_bf16_f32 v34, v50, v156
	v_cvt_pk_bf16_f32 v35, v51, v157
	v_cvt_pk_bf16_f32 v36, v52, v54
	v_cvt_pk_bf16_f32 v37, v53, v55
	v_pk_add_f32 v[50:51], v[64:65], v[172:173]
	v_pk_add_f32 v[52:53], v[158:159], v[174:175]
	v_pk_add_f32 v[50:51], v[160:161], v[50:51]
	v_pk_add_f32 v[52:53], v[162:163], v[52:53]
	v_pk_add_f32 v[50:51], v[164:165], v[50:51]
	v_pk_add_f32 v[52:53], v[166:167], v[52:53]
	v_pk_add_f32 v[50:51], v[168:169], v[50:51]
	v_pk_add_f32 v[52:53], v[170:171], v[52:53]
	v_readlane_b32 s66, v214, 2
	v_pk_add_f32 v[50:51], v[50:51], v[52:53]
	s_mov_b32 s50, 0x10000
	s_mov_b32 s51, 0x20000
	s_mov_b32 s52, 0x30000
	s_mov_b32 s53, 0xfffffc0
	s_movk_i32 s55, 0x110
	s_mov_b64 s[28:29], 0x1000
	s_mov_b32 s16, s10
	v_cvt_pk_bf16_f32 v38, v64, v158
	v_cvt_pk_bf16_f32 v39, v65, v159
	v_cvt_pk_bf16_f32 v40, v160, v162
	v_cvt_pk_bf16_f32 v41, v161, v163
	v_cvt_pk_bf16_f32 v42, v56, v58
	v_cvt_pk_bf16_f32 v43, v57, v59
	v_cvt_pk_bf16_f32 v44, v60, v62
	v_cvt_pk_bf16_f32 v45, v61, v63
	v_cvt_pk_bf16_f32 v46, v164, v166
	v_cvt_pk_bf16_f32 v47, v165, v167
	v_cvt_pk_bf16_f32 v48, v168, v170
	v_cvt_pk_bf16_f32 v49, v169, v171
	v_add_f32_e32 v50, v50, v51
	s_setprio 1
	v_mfma_f32_32x32x16_bf16 v[18:33], v[122:125], v[34:37], v[18:33]
	v_add_f32_e32 v154, v154, v50
	v_mfma_f32_32x32x16_bf16 v[2:17], v[126:129], v[34:37], v[2:17]
	v_mfma_f32_32x32x16_bf16 v[18:33], v[114:117], v[42:45], v[18:33]
	v_mfma_f32_32x32x16_bf16 v[2:17], v[118:121], v[42:45], v[2:17]
	v_mfma_f32_32x32x16_bf16 v[18:33], v[106:109], v[38:41], v[18:33]
	v_mfma_f32_32x32x16_bf16 v[2:17], v[110:113], v[38:41], v[2:17]
	v_mfma_f32_32x32x16_bf16 v[18:33], v[102:105], v[46:49], v[18:33]
	v_mfma_f32_32x32x16_bf16 v[2:17], v[98:101], v[46:49], v[2:17]
	s_setprio 0
	s_movk_i32 s2, 0x6000
	v_add_co_u32_e32 v34, vcc, s2, v140
	s_waitcnt vmcnt(3)
	ds_write_b128 v151, v[82:85]
	v_addc_co_u32_e32 v35, vcc, 0, v141, vcc
	s_waitcnt vmcnt(1)
	ds_write_b128 v152, v[86:89]
	ds_write_b128 v132, v[90:93] offset:18432
	s_waitcnt vmcnt(0)
	ds_write_b128 v134, v[94:97] offset:18432
	s_waitcnt lgkmcnt(0)
	s_barrier
	global_load_dwordx4 v[82:85], v[34:35], off
	v_add_co_u32_e32 v34, vcc, s2, v142
	global_load_dwordx4 v[90:93], v[136:137], off offset:384
	s_nop 0
	v_addc_co_u32_e32 v35, vcc, 0, v143, vcc
	global_load_dwordx4 v[86:89], v[34:35], off
	global_load_dwordx4 v[94:97], v[138:139], off offset:384
	ds_read_b128 v[34:37], v0 offset:4608
	ds_read_b128 v[50:53], v0
	ds_read_b128 v[98:101], v0 offset:32
	ds_read_b128 v[54:57], v0 offset:4640
	ds_read_b128 v[102:105], v0 offset:64
	ds_read_b128 v[58:61], v0 offset:4672
	ds_read_b128 v[136:139], v0 offset:96
	ds_read_b128 v[62:65], v0 offset:4704
	s_setprio 1
	s_waitcnt lgkmcnt(7)
	v_mfma_f32_32x32x16_bf16 v[34:49], v[34:37], v[78:81], 0
	s_waitcnt lgkmcnt(4)
	v_mfma_f32_32x32x16_bf16 v[34:49], v[54:57], v[74:77], v[34:49]
	s_waitcnt lgkmcnt(2)
	v_mfma_f32_32x32x16_bf16 v[34:49], v[58:61], v[70:73], v[34:49]
	s_waitcnt lgkmcnt(0)
	v_mfma_f32_32x32x16_bf16 v[34:49], v[62:65], v[66:69], v[34:49]
	v_mfma_f32_32x32x16_bf16 v[50:65], v[50:53], v[78:81], 0
	ds_read_b128 v[122:125], v0 offset:18432
	ds_read_b128 v[114:117], v0 offset:18464
	ds_read_b128 v[126:129], v0 offset:23040
	ds_read_b128 v[118:121], v0 offset:23072
	ds_read_b128 v[106:109], v0 offset:18496
	ds_read_b128 v[110:113], v0 offset:23104
	v_mfma_f32_32x32x16_bf16 v[50:65], v[98:101], v[74:77], v[50:65]
	ds_read_b128 v[98:101], v0 offset:23136
	v_mfma_f32_32x32x16_bf16 v[50:65], v[102:105], v[70:73], v[50:65]
	ds_read_b128 v[102:105], v0 offset:18528
	v_mfma_f32_32x32x16_bf16 v[50:65], v[136:139], v[66:69], v[50:65]
	s_setprio 0
	s_nop 11
	v_max_f32_e32 v136, v51, v51
	v_max_f32_e32 v137, v50, v50
	v_max_f32_e32 v136, v137, v136
	v_max3_f32 v136, v136, v52, v53
	v_max3_f32 v136, v136, v54, v55
	v_max3_f32 v136, v136, v56, v57
	v_max3_f32 v136, v136, v58, v59
	v_max3_f32 v136, v136, v60, v61
	v_max3_f32 v136, v136, v62, v63
	v_max3_f32 v136, v136, v64, v65
	v_max3_f32 v136, v136, v34, v35
	v_max3_f32 v136, v136, v36, v37
	v_max3_f32 v136, v136, v38, v39
	v_max3_f32 v136, v136, v40, v41
	v_max3_f32 v136, v136, v42, v43
	v_max3_f32 v136, v136, v44, v45
	v_max3_f32 v136, v136, v46, v47
	v_max3_f32 v136, v136, v48, v49
	ds_bpermute_b32 v137, v133, v136
	s_waitcnt lgkmcnt(0)
	v_max_f32_e32 v137, v137, v137
	v_max_f32_e32 v136, v136, v137
	v_cmp_gt_f32_e32 vcc, v136, v153
	s_cbranch_vccz .LBB0_592
; template <int DK, int MODE> ...
;     ...
;         if (__any(mx > m + 8.f)) {
;           const float mnew = fmaxf(m, mx);
;           const float alpha = __builtin_amdgcn_exp2f(m - mnew);
;           m = mnew; lsum *= alpha;
; #pragma unroll
;           for (int e = 0; e < 16; ++e) { o0[e] *= alpha; o1[e] *= alpha; }
;         }
	v_max_f32_e32 v136, v136, v136
	v_max_f32_e32 v137, v135, v135
	v_max_f32_e32 v137, v137, v136
	v_sub_f32_e32 v135, v135, v137
	v_exp_f32_e32 v136, v135
	v_add_f32_e32 v153, 0x41000000, v137
	v_mov_b32_e32 v135, v137
	v_pk_mul_f32 v[32:33], v[32:33], v[136:137] op_sel_hi:[1,0]
	v_pk_mul_f32 v[30:31], v[30:31], v[136:137] op_sel_hi:[1,0]
	v_pk_mul_f32 v[28:29], v[28:29], v[136:137] op_sel_hi:[1,0]
	v_pk_mul_f32 v[26:27], v[26:27], v[136:137] op_sel_hi:[1,0]
	v_pk_mul_f32 v[24:25], v[24:25], v[136:137] op_sel_hi:[1,0]
	v_pk_mul_f32 v[22:23], v[22:23], v[136:137] op_sel_hi:[1,0]
	v_pk_mul_f32 v[20:21], v[20:21], v[136:137] op_sel_hi:[1,0]
	v_pk_mul_f32 v[18:19], v[18:19], v[136:137] op_sel_hi:[1,0]
	v_pk_mul_f32 v[16:17], v[16:17], v[136:137] op_sel_hi:[1,0]
	v_pk_mul_f32 v[14:15], v[14:15], v[136:137] op_sel_hi:[1,0]
	v_pk_mul_f32 v[12:13], v[12:13], v[136:137] op_sel_hi:[1,0]
	v_pk_mul_f32 v[10:11], v[10:11], v[136:137] op_sel_hi:[1,0]
	v_pk_mul_f32 v[8:9], v[8:9], v[136:137] op_sel_hi:[1,0]
	v_pk_mul_f32 v[6:7], v[6:7], v[136:137] op_sel_hi:[1,0]
	v_pk_mul_f32 v[4:5], v[4:5], v[136:137] op_sel_hi:[1,0]
	v_pk_mul_f32 v[2:3], v[2:3], v[136:137] op_sel_hi:[1,0]
	v_mul_f32_e32 v154, v154, v136
; #define MFMA(a, b, c) __builtin_amdgcn_mfma_f32_32x32x16_bf16((a), (b), (c), 0, 0, 0)
; DI unsigned pack2(float a, float b) { f32x2 v = {a, b}; return __builtin_bit_cast(unsigned, __builtin_convertvector(v, bf16v2)); }
; template <int DK, int MODE> ...
;     ...
;         float ps0 = 0.f, ps1 = 0.f, ps2 = 0.f, ps3 = 0.f;
; #pragma unroll
;         for (int e = 0; e < 16; e += 4) {
;           s0[e] = __builtin_amdgcn_exp2f(s0[e] - m); s0[e + 1] = __builtin_amdgcn_exp2f(s0[e + 1] - m); s0[e + 2] = __builtin_amdgcn_exp2f(s0[e + 2] - m); s0[e + 3] = __builtin_amdgcn_exp2f(s0[e + 3] - m);
;           ps0 += s0[e]; ps1 += s0[e + 1]; ps2 += s0[e + 2]; ps3 += s0[e + 3];
;         }
; #pragma unroll
;         for (int e = 0; e < 16; e += 4) {
;           s1[e] = __builtin_amdgcn_exp2f(s1[e] - m); s1[e + 1] = __builtin_amdgcn_exp2f(s1[e + 1] - m); s1[e + 2] = __builtin_amdgcn_exp2f(s1[e + 2] - m); s1[e + 3] = __builtin_amdgcn_exp2f(s1[e + 3] - m);
;           ps0 += s1[e]; ps1 += s1[e + 1]; ps2 += s1[e + 2]; ps3 += s1[e + 3];
;         }
;         lsum += (ps0 + ps1) + (ps2 + ps3);
;     ...
; #pragma unroll
;       for (int j = 0; j < 2; ++j) {
;         u32x4 a, b;
;         a.x = pack2(s0[8 * j], s0[8 * j + 1]); a.y = pack2(s0[8 * j + 2], s0[8 * j + 3]); a.z = pack2(s0[8 * j + 4], s0[8 * j + 5]); a.w = pack2(s0[8 * j + 6], s0[8 * j + 7]);
;         b.x = pack2(s1[8 * j], s1[8 * j + 1]); b.y = pack2(s1[8 * j + 2], s1[8 * j + 3]); b.z = pack2(s1[8 * j + 4], s1[8 * j + 5]); b.w = pack2(s1[8 * j + 6], s1[8 * j + 7]);
;         pf[j] = __builtin_bit_cast(bf16x8, a); pf[2 + j] = __builtin_bit_cast(bf16x8, b);
;       }
;       __builtin_amdgcn_s_setprio(1);
; #pragma unroll
;       for (int j = 0; j < 4; ++j) { o0 = MFMA(vf0[j], pf[j], o0); o1 = MFMA(vf1[j], pf[j], o1); }
;       __builtin_amdgcn_s_setprio(0);
;     }
;     __builtin_amdgcn_sched_barrier(0);
;     if (more) swrite(cur ^ 1);
;     if (MODE == 2) { const int done = __all(R == 0.f); if (lane == 0) sFlag[cur * 4 + wave] = done; }
;     __syncthreads();
.LBB0_592:
	v_sub_f32_e32 v51, v51, v135
	v_exp_f32_e32 v136, v51
	v_sub_f32_e32 v51, v52, v135
	v_sub_f32_e32 v52, v53, v135
	v_sub_f32_e32 v53, v55, v135
	v_sub_f32_e32 v55, v57, v135
	v_sub_f32_e32 v57, v59, v135
	v_sub_f32_e32 v59, v61, v135
	v_sub_f32_e32 v61, v63, v135
	v_sub_f32_e32 v34, v34, v135
	v_exp_f32_e32 v137, v52
	v_sub_f32_e32 v52, v54, v135
	v_exp_f32_e32 v54, v53
	v_sub_f32_e32 v53, v56, v135
	v_sub_f32_e32 v56, v58, v135
	v_exp_f32_e32 v58, v57
	v_sub_f32_e32 v57, v60, v135
	v_sub_f32_e32 v60, v62, v135
	v_exp_f32_e32 v62, v61
	v_sub_f32_e32 v61, v64, v135
	v_exp_f32_e32 v64, v34
	v_sub_f32_e32 v34, v35, v135
	v_exp_f32_e32 v138, v34
	v_sub_f32_e32 v34, v36, v135
	v_sub_f32_e32 v63, v65, v135
	v_exp_f32_e32 v65, v34
	v_sub_f32_e32 v34, v37, v135
	v_exp_f32_e32 v139, v34
	v_sub_f32_e32 v34, v38, v135
	v_exp_f32_e32 v140, v34
	v_sub_f32_e32 v34, v39, v135
	v_exp_f32_e32 v142, v34
	v_sub_f32_e32 v34, v40, v135
	v_exp_f32_e32 v141, v34
	v_sub_f32_e32 v34, v41, v135
	v_exp_f32_e32 v143, v34
	v_sub_f32_e32 v34, v42, v135
	v_exp_f32_e32 v156, v34
	v_sub_f32_e32 v34, v43, v135
	v_exp_f32_e32 v158, v34
	v_sub_f32_e32 v34, v44, v135
	v_sub_f32_e32 v50, v50, v135
	v_exp_f32_e32 v157, v34
	v_sub_f32_e32 v34, v45, v135
	v_exp_f32_e32 v50, v50
	v_exp_f32_e32 v51, v51
	v_exp_f32_e32 v159, v34
	v_sub_f32_e32 v34, v46, v135
	v_exp_f32_e32 v52, v52
	v_exp_f32_e32 v53, v53
	v_exp_f32_e32 v55, v55
	v_exp_f32_e32 v160, v34
	v_sub_f32_e32 v34, v47, v135
	v_exp_f32_e32 v56, v56
	v_exp_f32_e32 v57, v57
	v_exp_f32_e32 v59, v59
	v_exp_f32_e32 v162, v34
	v_sub_f32_e32 v34, v48, v135
	v_exp_f32_e32 v60, v60
	v_exp_f32_e32 v61, v61
	v_exp_f32_e32 v63, v63
	v_exp_f32_e32 v161, v34
	v_sub_f32_e32 v34, v49, v135
	v_exp_f32_e32 v163, v34
	v_pk_add_f32 v[34:35], v[50:51], 0 op_sel_hi:[1,0]
	v_pk_add_f32 v[36:37], v[136:137], 0 op_sel_hi:[1,0]
	v_pk_add_f32 v[34:35], v[52:53], v[34:35]
	v_pk_add_f32 v[36:37], v[54:55], v[36:37]
	v_pk_add_f32 v[34:35], v[56:57], v[34:35]
	v_pk_add_f32 v[36:37], v[58:59], v[36:37]
	v_pk_add_f32 v[164:165], v[60:61], v[34:35]
	v_pk_add_f32 v[166:167], v[62:63], v[36:37]
	v_cvt_pk_bf16_f32 v34, v50, v136
	v_cvt_pk_bf16_f32 v35, v51, v137
	v_cvt_pk_bf16_f32 v36, v52, v54
	v_cvt_pk_bf16_f32 v37, v53, v55
	v_pk_add_f32 v[50:51], v[64:65], v[164:165]
	v_pk_add_f32 v[52:53], v[138:139], v[166:167]
	v_pk_add_f32 v[50:51], v[140:141], v[50:51]
	v_pk_add_f32 v[52:53], v[142:143], v[52:53]
	v_pk_add_f32 v[50:51], v[156:157], v[50:51]
	v_pk_add_f32 v[52:53], v[158:159], v[52:53]
	v_pk_add_f32 v[50:51], v[160:161], v[50:51]
	v_pk_add_f32 v[52:53], v[162:163], v[52:53]
	v_cvt_pk_bf16_f32 v38, v64, v138
	v_pk_add_f32 v[50:51], v[50:51], v[52:53]
	v_cvt_pk_bf16_f32 v39, v65, v139
	v_cvt_pk_bf16_f32 v40, v140, v142
	v_cvt_pk_bf16_f32 v41, v141, v143
	v_cvt_pk_bf16_f32 v42, v56, v58
	v_cvt_pk_bf16_f32 v43, v57, v59
	v_cvt_pk_bf16_f32 v44, v60, v62
	v_cvt_pk_bf16_f32 v45, v61, v63
	v_cvt_pk_bf16_f32 v46, v156, v158
	v_cvt_pk_bf16_f32 v47, v157, v159
	v_cvt_pk_bf16_f32 v48, v160, v162
	v_cvt_pk_bf16_f32 v49, v161, v163
	v_add_f32_e32 v50, v50, v51
	s_setprio 1
	v_mfma_f32_32x32x16_bf16 v[18:33], v[122:125], v[34:37], v[18:33]
	v_mfma_f32_32x32x16_bf16 v[2:17], v[126:129], v[34:37], v[2:17]
	v_mfma_f32_32x32x16_bf16 v[18:33], v[114:117], v[42:45], v[18:33]
	v_mfma_f32_32x32x16_bf16 v[2:17], v[118:121], v[42:45], v[2:17]
	v_mfma_f32_32x32x16_bf16 v[18:33], v[106:109], v[38:41], v[18:33]
	v_mfma_f32_32x32x16_bf16 v[2:17], v[110:113], v[38:41], v[2:17]
	v_mfma_f32_32x32x16_bf16 v[18:33], v[102:105], v[46:49], v[18:33]
	v_add_f32_e32 v104, v154, v50
	v_mfma_f32_32x32x16_bf16 v[2:17], v[98:101], v[46:49], v[2:17]
	s_setprio 0
	s_waitcnt vmcnt(3)
	ds_write_b128 v151, v[82:85] offset:9216
	s_waitcnt vmcnt(1)
	ds_write_b128 v152, v[86:89] offset:9216
	ds_write_b128 v132, v[90:93] offset:27648
	s_waitcnt vmcnt(0)
	ds_write_b128 v134, v[94:97] offset:27648
	s_waitcnt lgkmcnt(0)
	s_barrier
	ds_read_b128 v[34:37], v0 offset:13824
	ds_read_b128 v[50:53], v0 offset:9216
	ds_read_b128 v[82:85], v0 offset:9248
	ds_read_b128 v[54:57], v0 offset:13856
	ds_read_b128 v[86:89], v0 offset:9280
	ds_read_b128 v[58:61], v0 offset:13888
	ds_read_b128 v[62:65], v0 offset:13920
	ds_read_b128 v[106:109], v0 offset:9312
	s_setprio 1
	s_waitcnt lgkmcnt(7)
	v_mfma_f32_32x32x16_bf16 v[34:49], v[34:37], v[78:81], 0
	s_waitcnt lgkmcnt(4)
	v_mfma_f32_32x32x16_bf16 v[34:49], v[54:57], v[74:77], v[34:49]
	s_waitcnt lgkmcnt(2)
	v_mfma_f32_32x32x16_bf16 v[34:49], v[58:61], v[70:73], v[34:49]
	s_waitcnt lgkmcnt(1)
	v_mfma_f32_32x32x16_bf16 v[34:49], v[62:65], v[66:69], v[34:49]
	v_mfma_f32_32x32x16_bf16 v[50:65], v[50:53], v[78:81], 0
	ds_read_b128 v[98:101], v0 offset:27648
	ds_read_b128 v[90:93], v0 offset:27680
	ds_read_b128 v[94:97], v0 offset:32256
	ds_read_b128 v[78:81], v0 offset:32320
	v_mfma_f32_32x32x16_bf16 v[50:65], v[82:85], v[74:77], v[50:65]
	ds_read_b128 v[82:85], v0 offset:27712
	ds_read_b128 v[74:77], v0 offset:27744
	v_mfma_f32_32x32x16_bf16 v[50:65], v[86:89], v[70:73], v[50:65]
	ds_read_b128 v[86:89], v0 offset:32288
	ds_read_b128 v[70:73], v0 offset:32352
	s_waitcnt lgkmcnt(8)
	v_mfma_f32_32x32x16_bf16 v[50:65], v[106:109], v[66:69], v[50:65]
	s_setprio 0
	s_nop 11
	v_max_f32_e32 v0, v51, v51
	v_max_f32_e32 v66, v50, v50
	v_max_f32_e32 v0, v66, v0
	v_max3_f32 v0, v0, v52, v53
	v_max3_f32 v0, v0, v54, v55
	v_max3_f32 v0, v0, v56, v57
	v_max3_f32 v0, v0, v58, v59
	v_max3_f32 v0, v0, v60, v61
	v_max3_f32 v0, v0, v62, v63
	v_max3_f32 v0, v0, v64, v65
	v_max3_f32 v0, v0, v34, v35
	v_max3_f32 v0, v0, v36, v37
	v_max3_f32 v0, v0, v38, v39
	v_max3_f32 v0, v0, v40, v41
	v_max3_f32 v0, v0, v42, v43
	v_max3_f32 v0, v0, v44, v45
	v_max3_f32 v0, v0, v46, v47
	v_max3_f32 v0, v0, v48, v49
	ds_bpermute_b32 v66, v133, v0
	s_waitcnt lgkmcnt(0)
	v_max_f32_e32 v66, v66, v66
	v_max_f32_e32 v0, v0, v66
	v_cmp_gt_f32_e32 vcc, v0, v153
	s_cbranch_vccz .LBB0_573
	v_max_f32_e32 v0, v0, v0
	v_max_f32_e32 v66, v135, v135
	v_max_f32_e32 v66, v66, v0
	v_sub_f32_e32 v0, v135, v66
	v_exp_f32_e32 v0, v0
	v_mov_b32_e32 v135, v66
	v_pk_mul_f32 v[32:33], v[32:33], v[0:1] op_sel_hi:[1,0]
	v_pk_mul_f32 v[30:31], v[30:31], v[0:1] op_sel_hi:[1,0]
	v_pk_mul_f32 v[28:29], v[28:29], v[0:1] op_sel_hi:[1,0]
	v_pk_mul_f32 v[26:27], v[26:27], v[0:1] op_sel_hi:[1,0]
	v_pk_mul_f32 v[24:25], v[24:25], v[0:1] op_sel_hi:[1,0]
	v_pk_mul_f32 v[22:23], v[22:23], v[0:1] op_sel_hi:[1,0]
	v_pk_mul_f32 v[20:21], v[20:21], v[0:1] op_sel_hi:[1,0]
	v_pk_mul_f32 v[18:19], v[18:19], v[0:1] op_sel_hi:[1,0]
	v_pk_mul_f32 v[16:17], v[16:17], v[0:1] op_sel_hi:[1,0]
	v_pk_mul_f32 v[14:15], v[14:15], v[0:1] op_sel_hi:[1,0]
	v_pk_mul_f32 v[12:13], v[12:13], v[0:1] op_sel_hi:[1,0]
	v_pk_mul_f32 v[10:11], v[10:11], v[0:1] op_sel_hi:[1,0]
	v_pk_mul_f32 v[8:9], v[8:9], v[0:1] op_sel_hi:[1,0]
	v_pk_mul_f32 v[6:7], v[6:7], v[0:1] op_sel_hi:[1,0]
	v_pk_mul_f32 v[4:5], v[4:5], v[0:1] op_sel_hi:[1,0]
	v_pk_mul_f32 v[2:3], v[2:3], v[0:1] op_sel_hi:[1,0]
	v_mul_f32_e32 v104, v104, v0
	s_branch .LBB0_573
